# pool part: window/slide/gate LDS reads issued ahead through one in-order queue (counted lgkmcnt), gate reads hoisted out of the final stage; on top of convpipe+sched
# baseline (speedup 1.0000x reference)
.LBB0_613:
	s_or_b64 exec, exec, s[26:27]
	v_bfe_u32 v32, v50, 3, 2
	v_ashrrev_i32_e32 v29, 3, v50
	v_lshlrev_b32_e64 v25, v32, 1
	v_and_b32_e32 v31, -4, v29
	v_and_b32_e32 v24, 31, v50
	v_sub_u32_e32 v8, v31, v25
	v_lshlrev_b32_e32 v8, 9, v8
	v_lshlrev_b32_e32 v28, 4, v24
	v_readlane_b32 s23, v254, 38
	v_cmp_lt_u32_e32 vcc, 7, v24
	s_nop 0
	v_add3_u32 v12, v8, s23, v28
	ds_read_b128 v[8:11], v12 offset:4096
	ds_read_b128 v[34:37], v12 offset:4608
	v_add_u32_e32 v30, 0x1000, v12
	v_cmp_lt_u32_e64 s[66:67], 7, v24
	v_cmp_lt_u32_e64 s[68:69], 15, v24
	v_cmp_eq_u32_e64 s[70:71], 3, v32
	s_mov_b64 s[72:73], exec
	s_movk_i32 s74, 0x200
	s_movk_i32 s75, 0x400
	v_lshl_add_u32 v96, s74, v32, v30
	v_lshl_add_u32 v97, s75, v32, v30
	v_or_b32_e32 v138, s43, v49
	v_or_b32_e32 v138, s42, v138
	v_lshlrev_b32_e32 v138, 1, v138
	v_mul_u32_u24_e32 v139, 0x840, v48
	v_add_u32_e32 v138, v138, v139
	s_mov_b64 exec, s[66:67]
	ds_read_b128 v[154:157], v30 offset:1024
	ds_read_b128 v[158:161], v30 offset:1536
	s_mov_b64 exec, s[68:69]
	ds_read_b128 v[162:165], v30 offset:2048
	ds_read_b128 v[166:169], v30 offset:2560
	ds_read_b128 v[170:173], v30 offset:3072
	ds_read_b128 v[174:177], v30 offset:3584
	s_mov_b64 exec, s[70:71]
	ds_read_b128 v[178:181], v30 offset:4096
	ds_read_b128 v[182:185], v30 offset:4608
	ds_read_b128 v[186:189], v30 offset:5120
	ds_read_b128 v[190:193], v30 offset:5632
	ds_read_b128 v[194:197], v30 offset:6144
	ds_read_b128 v[198:201], v30 offset:6656
	ds_read_b128 v[202:205], v30 offset:7168
	s_mov_b64 exec, s[72:73]
	s_waitcnt lgkmcnt(14)
	v_lshlrev_b32_e32 v12, 16, v8
	v_and_b32_e32 v13, 0xffff0000, v8
	v_lshlrev_b32_e32 v14, 16, v10
	v_and_b32_e32 v15, 0xffff0000, v10
	v_lshlrev_b32_e32 v10, 16, v11
	v_and_b32_e32 v11, 0xffff0000, v11
	v_pk_add_f32 v[12:13], v[12:13], 0 op_sel_hi:[1,0]
	v_lshlrev_b32_e32 v8, 16, v9
	v_and_b32_e32 v9, 0xffff0000, v9
	v_pk_add_f32 v[38:39], v[10:11], 0 op_sel_hi:[1,0]
	s_waitcnt lgkmcnt(13)
	v_lshlrev_b32_e32 v10, 16, v34
	v_and_b32_e32 v11, 0xffff0000, v34
	v_pk_add_f32 v[8:9], v[8:9], 0 op_sel_hi:[1,0]
	v_pk_add_f32 v[26:27], v[14:15], 0 op_sel_hi:[1,0]
	v_pk_add_f32 v[14:15], v[12:13], v[10:11]
	v_lshlrev_b32_e32 v10, 16, v35
	v_and_b32_e32 v11, 0xffff0000, v35
	v_pk_add_f32 v[12:13], v[8:9], v[10:11]
	v_lshlrev_b32_e32 v8, 16, v36
	v_and_b32_e32 v9, 0xffff0000, v36
	v_pk_add_f32 v[10:11], v[26:27], v[8:9]
	v_lshlrev_b32_e32 v8, 16, v37
	v_and_b32_e32 v9, 0xffff0000, v37
	v_pk_add_f32 v[8:9], v[38:39], v[8:9]
	s_mov_b64 exec, s[70:71]
	ds_read_b128 v[206:209], v30 offset:7680
	s_mov_b64 exec, s[72:73]
	ds_read_b128 v[98:101], v96
	s_mov_b64 exec, s[66:67]
	s_waitcnt lgkmcnt(14)
	v_lshlrev_b32_e32 v26, 16, v154
	v_and_b32_e32 v27, 0xffff0000, v154
	v_pk_add_f32 v[14:15], v[14:15], v[26:27]
	v_lshlrev_b32_e32 v26, 16, v155
	v_and_b32_e32 v27, 0xffff0000, v155
	v_pk_add_f32 v[12:13], v[12:13], v[26:27]
	v_lshlrev_b32_e32 v26, 16, v156
	v_and_b32_e32 v27, 0xffff0000, v156
	v_pk_add_f32 v[10:11], v[10:11], v[26:27]
	v_lshlrev_b32_e32 v26, 16, v157
	v_and_b32_e32 v27, 0xffff0000, v157
	v_pk_add_f32 v[8:9], v[8:9], v[26:27]
	s_waitcnt lgkmcnt(13)
	v_lshlrev_b32_e32 v26, 16, v158
	v_and_b32_e32 v27, 0xffff0000, v158
	v_pk_add_f32 v[14:15], v[14:15], v[26:27]
	v_lshlrev_b32_e32 v26, 16, v159
	v_and_b32_e32 v27, 0xffff0000, v159
	v_pk_add_f32 v[12:13], v[12:13], v[26:27]
	v_lshlrev_b32_e32 v26, 16, v160
	v_and_b32_e32 v27, 0xffff0000, v160
	v_pk_add_f32 v[10:11], v[10:11], v[26:27]
	v_lshlrev_b32_e32 v26, 16, v161
	v_and_b32_e32 v27, 0xffff0000, v161
	v_pk_add_f32 v[8:9], v[8:9], v[26:27]
	s_mov_b64 exec, s[72:73]
	ds_read_u16 v64, v138 offset:33792
	ds_read_u16 v65, v138 offset:34320
	s_mov_b64 exec, s[68:69]
	s_waitcnt lgkmcnt(14)
	v_lshlrev_b32_e32 v26, 16, v162
	v_and_b32_e32 v27, 0xffff0000, v162
	v_pk_add_f32 v[14:15], v[14:15], v[26:27]
	v_lshlrev_b32_e32 v26, 16, v163
	v_and_b32_e32 v27, 0xffff0000, v163
	v_pk_add_f32 v[12:13], v[12:13], v[26:27]
	v_lshlrev_b32_e32 v26, 16, v164
	v_and_b32_e32 v27, 0xffff0000, v164
	v_pk_add_f32 v[10:11], v[10:11], v[26:27]
	v_lshlrev_b32_e32 v26, 16, v165
	v_and_b32_e32 v27, 0xffff0000, v165
	v_pk_add_f32 v[8:9], v[8:9], v[26:27]
	s_waitcnt lgkmcnt(13)
	v_lshlrev_b32_e32 v26, 16, v166
	v_and_b32_e32 v27, 0xffff0000, v166
	v_pk_add_f32 v[14:15], v[14:15], v[26:27]
	v_lshlrev_b32_e32 v26, 16, v167
	v_and_b32_e32 v27, 0xffff0000, v167
	v_pk_add_f32 v[12:13], v[12:13], v[26:27]
	v_lshlrev_b32_e32 v26, 16, v168
	v_and_b32_e32 v27, 0xffff0000, v168
	v_pk_add_f32 v[10:11], v[10:11], v[26:27]
	v_lshlrev_b32_e32 v26, 16, v169
	v_and_b32_e32 v27, 0xffff0000, v169
	v_pk_add_f32 v[8:9], v[8:9], v[26:27]
	s_waitcnt lgkmcnt(12)
	v_lshlrev_b32_e32 v26, 16, v170
	v_and_b32_e32 v27, 0xffff0000, v170
	v_pk_add_f32 v[14:15], v[14:15], v[26:27]
	v_lshlrev_b32_e32 v26, 16, v171
	v_and_b32_e32 v27, 0xffff0000, v171
	v_pk_add_f32 v[12:13], v[12:13], v[26:27]
	v_lshlrev_b32_e32 v26, 16, v172
	v_and_b32_e32 v27, 0xffff0000, v172
	v_pk_add_f32 v[10:11], v[10:11], v[26:27]
	v_lshlrev_b32_e32 v26, 16, v173
	v_and_b32_e32 v27, 0xffff0000, v173
	v_pk_add_f32 v[8:9], v[8:9], v[26:27]
	s_waitcnt lgkmcnt(11)
	v_lshlrev_b32_e32 v26, 16, v174
	v_and_b32_e32 v27, 0xffff0000, v174
	v_pk_add_f32 v[14:15], v[14:15], v[26:27]
	v_lshlrev_b32_e32 v26, 16, v175
	v_and_b32_e32 v27, 0xffff0000, v175
	v_pk_add_f32 v[12:13], v[12:13], v[26:27]
	v_lshlrev_b32_e32 v26, 16, v176
	v_and_b32_e32 v27, 0xffff0000, v176
	v_pk_add_f32 v[10:11], v[10:11], v[26:27]
	v_lshlrev_b32_e32 v26, 16, v177
	v_and_b32_e32 v27, 0xffff0000, v177
	v_pk_add_f32 v[8:9], v[8:9], v[26:27]
	s_mov_b64 exec, s[72:73]
	ds_read_u16 v66, v138 offset:34848
	ds_read_b128 v[102:105], v30
	ds_read_u16 v67, v138 offset:42240
	ds_read_u16 v68, v138 offset:35376
	s_mov_b64 exec, s[70:71]
	s_waitcnt lgkmcnt(14)
	v_lshlrev_b32_e32 v26, 16, v178
	v_and_b32_e32 v27, 0xffff0000, v178
	v_pk_add_f32 v[14:15], v[14:15], v[26:27]
	v_lshlrev_b32_e32 v26, 16, v179
	v_and_b32_e32 v27, 0xffff0000, v179
	v_pk_add_f32 v[12:13], v[12:13], v[26:27]
	v_lshlrev_b32_e32 v26, 16, v180
	v_and_b32_e32 v27, 0xffff0000, v180
	v_pk_add_f32 v[10:11], v[10:11], v[26:27]
	v_lshlrev_b32_e32 v26, 16, v181
	v_and_b32_e32 v27, 0xffff0000, v181
	v_pk_add_f32 v[8:9], v[8:9], v[26:27]
	s_waitcnt lgkmcnt(13)
	v_lshlrev_b32_e32 v26, 16, v182
	v_and_b32_e32 v27, 0xffff0000, v182
	v_pk_add_f32 v[14:15], v[14:15], v[26:27]
	v_lshlrev_b32_e32 v26, 16, v183
	v_and_b32_e32 v27, 0xffff0000, v183
	v_pk_add_f32 v[12:13], v[12:13], v[26:27]
	v_lshlrev_b32_e32 v26, 16, v184
	v_and_b32_e32 v27, 0xffff0000, v184
	v_pk_add_f32 v[10:11], v[10:11], v[26:27]
	v_lshlrev_b32_e32 v26, 16, v185
	v_and_b32_e32 v27, 0xffff0000, v185
	v_pk_add_f32 v[8:9], v[8:9], v[26:27]
	s_waitcnt lgkmcnt(12)
	v_lshlrev_b32_e32 v26, 16, v186
	v_and_b32_e32 v27, 0xffff0000, v186
	v_pk_add_f32 v[14:15], v[14:15], v[26:27]
	v_lshlrev_b32_e32 v26, 16, v187
	v_and_b32_e32 v27, 0xffff0000, v187
	v_pk_add_f32 v[12:13], v[12:13], v[26:27]
	v_lshlrev_b32_e32 v26, 16, v188
	v_and_b32_e32 v27, 0xffff0000, v188
	v_pk_add_f32 v[10:11], v[10:11], v[26:27]
	v_lshlrev_b32_e32 v26, 16, v189
	v_and_b32_e32 v27, 0xffff0000, v189
	v_pk_add_f32 v[8:9], v[8:9], v[26:27]
	s_waitcnt lgkmcnt(11)
	v_lshlrev_b32_e32 v26, 16, v190
	v_and_b32_e32 v27, 0xffff0000, v190
	v_pk_add_f32 v[14:15], v[14:15], v[26:27]
	v_lshlrev_b32_e32 v26, 16, v191
	v_and_b32_e32 v27, 0xffff0000, v191
	v_pk_add_f32 v[12:13], v[12:13], v[26:27]
	v_lshlrev_b32_e32 v26, 16, v192
	v_and_b32_e32 v27, 0xffff0000, v192
	v_pk_add_f32 v[10:11], v[10:11], v[26:27]
	v_lshlrev_b32_e32 v26, 16, v193
	v_and_b32_e32 v27, 0xffff0000, v193
	v_pk_add_f32 v[8:9], v[8:9], v[26:27]
	s_waitcnt lgkmcnt(10)
	v_lshlrev_b32_e32 v26, 16, v194
	v_and_b32_e32 v27, 0xffff0000, v194
	v_pk_add_f32 v[14:15], v[14:15], v[26:27]
	v_lshlrev_b32_e32 v26, 16, v195
	v_and_b32_e32 v27, 0xffff0000, v195
	v_pk_add_f32 v[12:13], v[12:13], v[26:27]
	v_lshlrev_b32_e32 v26, 16, v196
	v_and_b32_e32 v27, 0xffff0000, v196
	v_pk_add_f32 v[10:11], v[10:11], v[26:27]
	v_lshlrev_b32_e32 v26, 16, v197
	v_and_b32_e32 v27, 0xffff0000, v197
	v_pk_add_f32 v[8:9], v[8:9], v[26:27]
	s_waitcnt lgkmcnt(9)
	v_lshlrev_b32_e32 v26, 16, v198
	v_and_b32_e32 v27, 0xffff0000, v198
	v_pk_add_f32 v[14:15], v[14:15], v[26:27]
	v_lshlrev_b32_e32 v26, 16, v199
	v_and_b32_e32 v27, 0xffff0000, v199
	v_pk_add_f32 v[12:13], v[12:13], v[26:27]
	v_lshlrev_b32_e32 v26, 16, v200
	v_and_b32_e32 v27, 0xffff0000, v200
	v_pk_add_f32 v[10:11], v[10:11], v[26:27]
	v_lshlrev_b32_e32 v26, 16, v201
	v_and_b32_e32 v27, 0xffff0000, v201
	v_pk_add_f32 v[8:9], v[8:9], v[26:27]
	s_waitcnt lgkmcnt(8)
	v_lshlrev_b32_e32 v26, 16, v202
	v_and_b32_e32 v27, 0xffff0000, v202
	v_pk_add_f32 v[14:15], v[14:15], v[26:27]
	v_lshlrev_b32_e32 v26, 16, v203
	v_and_b32_e32 v27, 0xffff0000, v203
	v_pk_add_f32 v[12:13], v[12:13], v[26:27]
	v_lshlrev_b32_e32 v26, 16, v204
	v_and_b32_e32 v27, 0xffff0000, v204
	v_pk_add_f32 v[10:11], v[10:11], v[26:27]
	v_lshlrev_b32_e32 v26, 16, v205
	v_and_b32_e32 v27, 0xffff0000, v205
	v_pk_add_f32 v[8:9], v[8:9], v[26:27]
	s_waitcnt lgkmcnt(7)
	v_lshlrev_b32_e32 v26, 16, v206
	v_and_b32_e32 v27, 0xffff0000, v206
	v_pk_add_f32 v[14:15], v[14:15], v[26:27]
	v_lshlrev_b32_e32 v26, 16, v207
	v_and_b32_e32 v27, 0xffff0000, v207
	v_pk_add_f32 v[12:13], v[12:13], v[26:27]
	v_lshlrev_b32_e32 v26, 16, v208
	v_and_b32_e32 v27, 0xffff0000, v208
	v_pk_add_f32 v[10:11], v[10:11], v[26:27]
	v_lshlrev_b32_e32 v26, 16, v209
	v_and_b32_e32 v27, 0xffff0000, v209
	v_pk_add_f32 v[8:9], v[8:9], v[26:27]
	s_mov_b64 exec, s[72:73]
	ds_read_u16 v69, v138 offset:42768
	ds_read_b128 v[106:109], v97
	ds_read_u16 v70, v138 offset:43296
	ds_read_u16 v71, v138 offset:50688
	ds_read_u16 v72, v138 offset:43824
	ds_read_b128 v[110:113], v96 offset:512
	ds_read_u16 v73, v138 offset:59136
	ds_read_u16 v74, v138 offset:33824
	v_add_u32_e32 v26, s47, v31
	v_sub_u32_e32 v27, v26, v25
	v_add_u32_e32 v26, v26, v25
	v_max_i32_e32 v27, 0, v27
	v_min_i32_e32 v26, s46, v26
	v_sub_u32_e32 v26, v26, v27
	v_cvt_f32_i32_e32 v26, v26
	v_lshlrev_b32_e32 v33, 9, v31
	v_readlane_b32 s49, v254, 38
	v_add_u32_e32 v24, 0, v28
	v_div_scale_f32 v27, s[26:27], v26, v26, 1.0
	v_add3_u32 v33, s49, v33, v28
	s_waitcnt lgkmcnt(14)
	v_mov_b32_e32 v34, v98
	v_mov_b32_e32 v35, v99
	v_mov_b32_e32 v36, v100
	v_mov_b32_e32 v37, v101
	v_rcp_f32_e32 v33, v27
	s_movk_i32 s48, 0x210
	s_movk_i32 s23, 0x400
	v_lshl_add_u32 v45, s23, v32, v30
	v_fma_f32 v38, -v27, v33, 1.0
	v_fmac_f32_e32 v33, v38, v33
	v_div_scale_f32 v38, vcc, 1.0, v26, 1.0
	v_mul_f32_e32 v39, v38, v33
	v_fma_f32 v40, -v27, v39, v38
	v_fmac_f32_e32 v39, v40, v33
	v_fma_f32 v27, -v27, v39, v38
	v_div_fmas_f32 v27, v27, v33, v39
	v_div_fixup_f32 v26, v27, v26, 1.0
	v_lshlrev_b32_e32 v38, 16, v34
	v_and_b32_e32 v39, 0xffff0000, v34
	v_pk_fma_f32 v[38:39], v[26:27], v[14:15], v[38:39] op_sel_hi:[0,1,1] neg_lo:[0,0,1] neg_hi:[0,0,1]
	v_cvt_pk_bf16_f32 v34, v38, v39
	v_lshlrev_b32_e32 v38, 16, v35
	v_and_b32_e32 v39, 0xffff0000, v35
	v_pk_fma_f32 v[38:39], v[26:27], v[12:13], v[38:39] op_sel_hi:[0,1,1] neg_lo:[0,0,1] neg_hi:[0,0,1]
	v_cvt_pk_bf16_f32 v35, v38, v39
	v_lshlrev_b32_e32 v38, 16, v36
	v_and_b32_e32 v39, 0xffff0000, v36
	v_pk_fma_f32 v[38:39], v[26:27], v[10:11], v[38:39] op_sel_hi:[0,1,1] neg_lo:[0,0,1] neg_hi:[0,0,1]
	v_cvt_pk_bf16_f32 v36, v38, v39
	v_lshlrev_b32_e32 v38, 16, v37
	v_and_b32_e32 v39, 0xffff0000, v37
	v_pk_fma_f32 v[26:27], v[26:27], v[8:9], v[38:39] op_sel_hi:[0,1,1] neg_lo:[0,0,1] neg_hi:[0,0,1]
	v_cvt_pk_bf16_f32 v37, v26, v27
	v_mad_u64_u32 v[26:27], s[26:27], v31, s48, v[24:25]
	ds_write_b128 v26, v[34:37]
	s_waitcnt lgkmcnt(11)
	v_mov_b32_e32 v34, v102
	v_mov_b32_e32 v35, v103
	v_mov_b32_e32 v36, v104
	v_mov_b32_e32 v37, v105
	ds_read_u16 v75, v138 offset:59664
	ds_read_b128 v[114:117], v30 offset:512
	ds_read_u16 v76, v138 offset:51216
	s_waitcnt lgkmcnt(10)
	v_mov_b32_e32 v38, v106
	v_mov_b32_e32 v39, v107
	v_mov_b32_e32 v40, v108
	v_mov_b32_e32 v41, v109
	ds_read_u16 v77, v138 offset:60192
	ds_read_u16 v78, v138 offset:60720
	ds_read_b128 v[118:121], v97 offset:512
	ds_read_u16 v79, v138 offset:34352
	v_or_b32_e32 v27, 1, v31
	v_add_u32_e32 v44, s47, v27
	v_or_b32_e32 v29, 3, v29
	v_lshlrev_b32_e32 v42, 16, v34
	v_lshlrev_b32_e32 v32, 16, v38
	v_and_b32_e32 v33, 0xffff0000, v38
	v_and_b32_e32 v43, 0xffff0000, v34
	v_pk_add_f32 v[32:33], v[32:33], v[42:43] neg_lo:[0,1] neg_hi:[0,1]
	v_lshlrev_b32_e32 v34, 16, v35
	v_pk_add_f32 v[32:33], v[14:15], v[32:33]
	v_lshlrev_b32_e32 v14, 16, v39
	v_and_b32_e32 v15, 0xffff0000, v39
	v_and_b32_e32 v35, 0xffff0000, v35
	v_pk_add_f32 v[14:15], v[14:15], v[34:35] neg_lo:[0,1] neg_hi:[0,1]
	s_and_b32 s23, s45, 0xffffff80
	v_pk_add_f32 v[34:35], v[12:13], v[14:15]
	v_lshlrev_b32_e32 v12, 16, v40
	v_and_b32_e32 v13, 0xffff0000, v40
	v_lshlrev_b32_e32 v14, 16, v36
	v_and_b32_e32 v15, 0xffff0000, v36
	v_pk_add_f32 v[12:13], v[12:13], v[14:15] neg_lo:[0,1] neg_hi:[0,1]
	v_mul_u32_u24_e32 v56, 0x840, v48
	v_pk_add_f32 v[38:39], v[10:11], v[12:13]
	v_lshlrev_b32_e32 v10, 16, v41
	v_and_b32_e32 v11, 0xffff0000, v41
	v_lshlrev_b32_e32 v12, 16, v37
	v_and_b32_e32 v13, 0xffff0000, v37
	v_pk_add_f32 v[10:11], v[10:11], v[12:13] neg_lo:[0,1] neg_hi:[0,1]
	s_add_i32 s23, s23, 0
	v_pk_add_f32 v[36:37], v[8:9], v[10:11]
	v_sub_u32_e32 v8, v44, v25
	v_max_i32_e32 v12, 0, v8
	v_add_u32_e32 v8, v44, v25
	v_min_i32_e32 v13, s46, v8
	v_sub_u32_e32 v12, v13, v12
	v_cvt_f32_i32_e32 v12, v12
	v_lshlrev_b32_e32 v8, 9, v27
	v_add3_u32 v8, s49, v8, v28
	s_waitcnt lgkmcnt(10)
	v_mov_b32_e32 v8, v110
	v_mov_b32_e32 v9, v111
	v_mov_b32_e32 v10, v112
	v_mov_b32_e32 v11, v113
	ds_read_u16 v80, v138 offset:34880
	ds_read_u16 v81, v138 offset:42272
	ds_read_b128 v[122:125], v96 offset:1024
	ds_read_u16 v82, v138 offset:51744
	v_div_scale_f32 v13, s[26:27], v12, v12, 1.0
	v_rcp_f32_e32 v14, v13
	s_nop 0
	v_fma_f32 v15, -v13, v14, 1.0
	v_fmac_f32_e32 v14, v15, v14
	v_div_scale_f32 v15, vcc, 1.0, v12, 1.0
	v_mul_f32_e32 v27, v15, v14
	v_fma_f32 v40, -v13, v27, v15
	v_fmac_f32_e32 v27, v40, v14
	v_fma_f32 v13, -v13, v27, v15
	v_div_fmas_f32 v13, v13, v14, v27
	v_div_fixup_f32 v12, v13, v12, 1.0
	v_lshlrev_b32_e32 v14, 16, v8
	v_and_b32_e32 v15, 0xffff0000, v8
	v_pk_fma_f32 v[14:15], v[12:13], v[32:33], v[14:15] op_sel_hi:[0,1,1] neg_lo:[0,0,1] neg_hi:[0,0,1]
	v_cvt_pk_bf16_f32 v8, v14, v15
	v_lshlrev_b32_e32 v14, 16, v9
	v_and_b32_e32 v15, 0xffff0000, v9
	v_pk_fma_f32 v[14:15], v[12:13], v[34:35], v[14:15] op_sel_hi:[0,1,1] neg_lo:[0,0,1] neg_hi:[0,0,1]
	v_cvt_pk_bf16_f32 v9, v14, v15
	v_lshlrev_b32_e32 v14, 16, v10
	v_and_b32_e32 v15, 0xffff0000, v10
	v_pk_fma_f32 v[14:15], v[12:13], v[38:39], v[14:15] op_sel_hi:[0,1,1] neg_lo:[0,0,1] neg_hi:[0,0,1]
	v_cvt_pk_bf16_f32 v10, v14, v15
	v_lshlrev_b32_e32 v14, 16, v11
	v_and_b32_e32 v15, 0xffff0000, v11
	v_pk_fma_f32 v[12:13], v[12:13], v[36:37], v[14:15] op_sel_hi:[0,1,1] neg_lo:[0,0,1] neg_hi:[0,0,1]
	v_cvt_pk_bf16_f32 v11, v12, v13
	ds_write_b128 v26, v[8:11] offset:528
	s_waitcnt lgkmcnt(10)
	v_mov_b32_e32 v8, v114
	v_mov_b32_e32 v9, v115
	v_mov_b32_e32 v10, v116
	v_mov_b32_e32 v11, v117
	ds_read_u16 v83, v138 offset:35408
	ds_read_u16 v84, v138 offset:52272
	ds_read_b128 v[126:129], v97 offset:1024
	ds_read_u16 v85, v138 offset:42800
	s_waitcnt lgkmcnt(10)
	v_mov_b32_e32 v12, v118
	v_mov_b32_e32 v13, v119
	v_mov_b32_e32 v14, v120
	v_mov_b32_e32 v15, v121
	ds_read_u16 v86, v138 offset:43328
	ds_read_u16 v87, v138 offset:50720
	ds_read_b128 v[130:133], v30 offset:1024
	ds_read_u16 v88, v138 offset:43856
	v_or_b32_e32 v27, 2, v31
	v_add_u32_e32 v31, s47, v27
	v_lshlrev_b32_e32 v42, 16, v8
	v_lshlrev_b32_e32 v40, 16, v12
	v_and_b32_e32 v41, 0xffff0000, v12
	v_and_b32_e32 v43, 0xffff0000, v8
	v_lshlrev_b32_e32 v12, 16, v13
	v_and_b32_e32 v13, 0xffff0000, v13
	v_lshlrev_b32_e32 v8, 16, v9
	v_and_b32_e32 v9, 0xffff0000, v9
	v_pk_add_f32 v[8:9], v[12:13], v[8:9] neg_lo:[0,1] neg_hi:[0,1]
	v_lshlrev_b32_e32 v12, 16, v10
	v_pk_add_f32 v[34:35], v[34:35], v[8:9]
	v_lshlrev_b32_e32 v8, 16, v14
	v_and_b32_e32 v9, 0xffff0000, v14
	v_and_b32_e32 v13, 0xffff0000, v10
	v_pk_add_f32 v[8:9], v[8:9], v[12:13] neg_lo:[0,1] neg_hi:[0,1]
	v_lshlrev_b32_e32 v10, 16, v11
	v_pk_add_f32 v[38:39], v[38:39], v[8:9]
	v_lshlrev_b32_e32 v8, 16, v15
	v_and_b32_e32 v9, 0xffff0000, v15
	v_and_b32_e32 v11, 0xffff0000, v11
	v_pk_add_f32 v[8:9], v[8:9], v[10:11] neg_lo:[0,1] neg_hi:[0,1]
	v_pk_add_f32 v[40:41], v[40:41], v[42:43] neg_lo:[0,1] neg_hi:[0,1]
	v_pk_add_f32 v[36:37], v[36:37], v[8:9]
	v_sub_u32_e32 v8, v31, v25
	v_max_i32_e32 v12, 0, v8
	v_add_u32_e32 v8, v31, v25
	v_min_i32_e32 v13, s46, v8
	v_sub_u32_e32 v12, v13, v12
	v_cvt_f32_i32_e32 v12, v12
	v_lshlrev_b32_e32 v8, 9, v27
	v_add3_u32 v8, s49, v8, v28
	s_waitcnt lgkmcnt(10)
	v_mov_b32_e32 v8, v122
	v_mov_b32_e32 v9, v123
	v_mov_b32_e32 v10, v124
	v_mov_b32_e32 v11, v125
	ds_read_u16 v89, v138 offset:51248
	ds_read_u16 v90, v138 offset:59168
	ds_read_b128 v[134:137], v96 offset:1536
	ds_read_u16 v91, v138 offset:51776
	v_div_scale_f32 v13, s[26:27], v12, v12, 1.0
	v_rcp_f32_e32 v14, v13
	v_pk_add_f32 v[32:33], v[32:33], v[40:41]
	v_fma_f32 v15, -v13, v14, 1.0
	v_fmac_f32_e32 v14, v15, v14
	v_div_scale_f32 v15, vcc, 1.0, v12, 1.0
	v_mul_f32_e32 v27, v15, v14
	v_fma_f32 v31, -v13, v27, v15
	v_fmac_f32_e32 v27, v31, v14
	v_fma_f32 v13, -v13, v27, v15
	v_div_fmas_f32 v13, v13, v14, v27
	v_div_fixup_f32 v12, v13, v12, 1.0
	v_lshlrev_b32_e32 v14, 16, v8
	v_and_b32_e32 v15, 0xffff0000, v8
	v_pk_fma_f32 v[14:15], v[12:13], v[32:33], v[14:15] op_sel_hi:[0,1,1] neg_lo:[0,0,1] neg_hi:[0,0,1]
	v_cvt_pk_bf16_f32 v8, v14, v15
	v_lshlrev_b32_e32 v14, 16, v9
	v_and_b32_e32 v15, 0xffff0000, v9
	v_pk_fma_f32 v[14:15], v[12:13], v[34:35], v[14:15] op_sel_hi:[0,1,1] neg_lo:[0,0,1] neg_hi:[0,0,1]
	v_cvt_pk_bf16_f32 v9, v14, v15
	v_lshlrev_b32_e32 v14, 16, v10
	v_and_b32_e32 v15, 0xffff0000, v10
	v_pk_fma_f32 v[14:15], v[12:13], v[38:39], v[14:15] op_sel_hi:[0,1,1] neg_lo:[0,0,1] neg_hi:[0,0,1]
	v_cvt_pk_bf16_f32 v10, v14, v15
	v_lshlrev_b32_e32 v14, 16, v11
	v_and_b32_e32 v15, 0xffff0000, v11
	v_pk_fma_f32 v[12:13], v[12:13], v[36:37], v[14:15] op_sel_hi:[0,1,1] neg_lo:[0,0,1] neg_hi:[0,0,1]
	v_cvt_pk_bf16_f32 v11, v12, v13
	ds_write_b128 v26, v[8:11] offset:1056
	s_waitcnt lgkmcnt(10)
	v_mov_b32_e32 v8, v126
	v_mov_b32_e32 v9, v127
	v_mov_b32_e32 v10, v128
	v_mov_b32_e32 v11, v129
	ds_read_u16 v92, v138 offset:59696
	ds_read_u16 v93, v138 offset:52304
	ds_read_u16 v94, v138 offset:60224
	ds_read_u16 v95, v138 offset:60752
	s_waitcnt lgkmcnt(10)
	v_mov_b32_e32 v12, v130
	v_mov_b32_e32 v13, v131
	v_mov_b32_e32 v14, v132
	v_mov_b32_e32 v15, v133
	v_lshlrev_b32_e32 v26, 16, v11
	v_and_b32_e32 v27, 0xffff0000, v11
	v_lshlrev_b32_e32 v30, 16, v15
	v_and_b32_e32 v31, 0xffff0000, v15
	v_pk_add_f32 v[26:27], v[26:27], v[30:31] neg_lo:[0,1] neg_hi:[0,1]
	v_lshlrev_b32_e32 v30, 16, v10
	v_and_b32_e32 v31, 0xffff0000, v10
	v_lshlrev_b32_e32 v10, 16, v14
	v_and_b32_e32 v11, 0xffff0000, v14
	v_pk_add_f32 v[10:11], v[30:31], v[10:11] neg_lo:[0,1] neg_hi:[0,1]
	v_lshlrev_b32_e32 v30, 16, v13
	v_pk_add_f32 v[14:15], v[38:39], v[10:11]
	v_lshlrev_b32_e32 v10, 16, v9
	v_and_b32_e32 v11, 0xffff0000, v9
	v_and_b32_e32 v31, 0xffff0000, v13
	v_pk_add_f32 v[10:11], v[10:11], v[30:31] neg_lo:[0,1] neg_hi:[0,1]
	v_and_b32_e32 v9, 0xffff0000, v12
	v_pk_add_f32 v[30:31], v[34:35], v[10:11]
	v_lshlrev_b32_e32 v10, 16, v8
	v_and_b32_e32 v11, 0xffff0000, v8
	v_lshlrev_b32_e32 v8, 16, v12
	v_pk_add_f32 v[8:9], v[10:11], v[8:9] neg_lo:[0,1] neg_hi:[0,1]
	v_pk_add_f32 v[26:27], v[36:37], v[26:27]
	v_pk_add_f32 v[12:13], v[32:33], v[8:9]
	v_add_u32_e32 v8, s47, v29
	v_sub_u32_e32 v9, v8, v25
	v_add_u32_e32 v8, v8, v25
	v_max_i32_e32 v32, 0, v9
	v_min_i32_e32 v25, s46, v8
	v_sub_u32_e32 v25, v25, v32
	v_cvt_f32_i32_e32 v25, v25
	v_lshlrev_b32_e32 v8, 9, v29
	v_add3_u32 v8, s49, v8, v28
	s_waitcnt lgkmcnt(6)
	v_mov_b32_e32 v8, v134
	v_mov_b32_e32 v9, v135
	v_mov_b32_e32 v10, v136
	v_mov_b32_e32 v11, v137
	v_div_scale_f32 v28, s[26:27], v25, v25, 1.0
	v_rcp_f32_e32 v32, v28
	s_nop 0
	v_fma_f32 v33, -v28, v32, 1.0
	v_fmac_f32_e32 v32, v33, v32
	v_div_scale_f32 v33, vcc, 1.0, v25, 1.0
	v_mul_f32_e32 v34, v33, v32
	v_fma_f32 v35, -v28, v34, v33
	v_fmac_f32_e32 v34, v35, v32
	v_fma_f32 v28, -v28, v34, v33
	v_div_fmas_f32 v28, v28, v32, v34
	v_div_fixup_f32 v28, v28, v25, 1.0
	v_lshlrev_b32_e32 v32, 16, v8
	v_and_b32_e32 v33, 0xffff0000, v8
	v_pk_fma_f32 v[12:13], v[28:29], v[12:13], v[32:33] op_sel_hi:[0,1,1] neg_lo:[0,0,1] neg_hi:[0,0,1]
	v_cvt_pk_bf16_f32 v8, v12, v13
	v_lshlrev_b32_e32 v12, 16, v9
	v_and_b32_e32 v13, 0xffff0000, v9
	v_pk_fma_f32 v[12:13], v[28:29], v[30:31], v[12:13] op_sel_hi:[0,1,1] neg_lo:[0,0,1] neg_hi:[0,0,1]
	v_cvt_pk_bf16_f32 v9, v12, v13
	v_lshlrev_b32_e32 v12, 16, v10
	v_and_b32_e32 v13, 0xffff0000, v10
	v_pk_fma_f32 v[12:13], v[28:29], v[14:15], v[12:13] op_sel_hi:[0,1,1] neg_lo:[0,0,1] neg_hi:[0,0,1]
	v_cvt_pk_bf16_f32 v10, v12, v13
	v_lshlrev_b32_e32 v12, 16, v11
	v_and_b32_e32 v13, 0xffff0000, v11
	v_pk_fma_f32 v[12:13], v[28:29], v[26:27], v[12:13] op_sel_hi:[0,1,1] neg_lo:[0,0,1] neg_hi:[0,0,1]
	v_cvt_pk_bf16_f32 v11, v12, v13
	v_mad_u64_u32 v[12:13], s[26:27], v29, s48, v[24:25]
	ds_write_b128 v12, v[8:11]
	v_mul_u32_u24_e32 v8, 0x210, v49
	v_or_b32_e32 v49, s43, v49
	v_or_b32_e32 v51, s42, v49
	v_add_u32_e32 v48, s24, v51
	v_ashrrev_i32_e32 v49, 31, v48
	v_add3_u32 v12, s23, v148, v8
	v_lshl_add_u64 v[48:49], v[48:49], 2, s[88:89]
	s_waitcnt lgkmcnt(0)
	s_barrier
	ds_read_b128 v[40:43], v12
	ds_read_b128 v[44:47], v12 offset:64
	ds_read_b128 v[32:35], v12 offset:8448
	ds_read_b128 v[36:39], v12 offset:8512
	ds_read_b128 v[24:27], v12 offset:16896
	ds_read_b128 v[28:31], v12 offset:16960
	ds_read_b128 v[8:11], v12 offset:25344
	ds_read_b128 v[12:15], v12 offset:25408
	global_load_dword v57, v[48:49], off
	v_lshlrev_b32_e32 v51, 1, v51
	v_add3_u32 v51, 0, v51, v56
	s_waitcnt vmcnt(4) lgkmcnt(7)
	v_mfma_f32_16x16x32_bf16 v[52:55], v[40:43], v[16:19], 0
	v_readlane_b32 s26, v255, 11
	v_readlane_b32 s27, v255, 12
	s_waitcnt lgkmcnt(0)
	v_lshlrev_b32_e32 v56, 16, v64
	v_mul_f32_e32 v58, 0xbfb8aa3b, v56
	v_exp_f32_e32 v58, v58
	s_waitcnt vmcnt(3)
	v_mfma_f32_16x16x32_bf16 v[52:55], v[44:47], v[20:23], v[52:55]
	v_add_f32_e32 v58, 1.0, v58
	v_rcp_f32_e32 v58, v58
	s_nop 0
	v_mul_f32_e32 v56, v58, v56
	s_waitcnt vmcnt(0)
	s_nop 2
	v_mul_f32_e32 v52, v57, v52
	v_mul_f32_e32 v52, v52, v56
	v_cvt_pk_bf16_f32 v52, v52, s0
	ds_write_b16 v51, v52 offset:33792
	s_nop 0
	v_mul_f32_e32 v53, v57, v53
	v_lshlrev_b32_e32 v52, 16, v65
	v_mul_f32_e32 v56, 0xbfb8aa3b, v52
	v_exp_f32_e32 v56, v56
	s_nop 0
	v_add_f32_e32 v56, 1.0, v56
	v_rcp_f32_e32 v56, v56
	s_nop 0
	v_mul_f32_e32 v52, v56, v52
	v_mul_f32_e32 v52, v53, v52
	v_cvt_pk_bf16_f32 v52, v52, s0
	ds_write_b16 v51, v52 offset:34320
	v_mul_f32_e32 v53, v57, v54
	v_lshlrev_b32_e32 v52, 16, v66
	v_mul_f32_e32 v54, 0xbfb8aa3b, v52
	v_exp_f32_e32 v54, v54
	s_nop 0
	v_lshlrev_b32_e32 v56, 16, v67
	v_mul_f32_e32 v58, 0xbfb8aa3b, v56
	v_exp_f32_e32 v58, v58
	v_add_f32_e32 v54, 1.0, v54
	v_rcp_f32_e32 v54, v54
	v_add_f32_e32 v58, 1.0, v58
	v_rcp_f32_e32 v58, v58
	v_mul_f32_e32 v52, v54, v52
	v_mul_f32_e32 v52, v53, v52
	v_cvt_pk_bf16_f32 v52, v52, s0
	ds_write_b16 v51, v52 offset:34848
	v_mul_f32_e32 v53, v57, v55
	v_mul_f32_e32 v56, v58, v56
	v_lshlrev_b32_e32 v52, 16, v68
	v_mul_f32_e32 v54, 0xbfb8aa3b, v52
	v_exp_f32_e32 v54, v54
	s_nop 0
	v_add_f32_e32 v54, 1.0, v54
	v_rcp_f32_e32 v54, v54
	s_nop 0
	v_mul_f32_e32 v52, v54, v52
	v_mul_f32_e32 v52, v53, v52
	v_cvt_pk_bf16_f32 v52, v52, s0
	ds_write_b16 v51, v52 offset:35376
	v_mfma_f32_16x16x32_bf16 v[52:55], v[32:35], v[16:19], 0
	v_mfma_f32_16x16x32_bf16 v[52:55], v[36:39], v[20:23], v[52:55]
	s_nop 7
	v_mul_f32_e32 v52, v57, v52
	v_mul_f32_e32 v52, v52, v56
	v_cvt_pk_bf16_f32 v52, v52, s0
	ds_write_b16 v51, v52 offset:42240
	s_nop 0
	v_mul_f32_e32 v53, v57, v53
	s_nop 0
	v_lshlrev_b32_e32 v52, 16, v69
	v_mul_f32_e32 v56, 0xbfb8aa3b, v52
	v_exp_f32_e32 v56, v56
	s_nop 0
	v_add_f32_e32 v56, 1.0, v56
	v_rcp_f32_e32 v56, v56
	s_nop 0
	v_mul_f32_e32 v52, v56, v52
	v_mul_f32_e32 v52, v53, v52
	v_cvt_pk_bf16_f32 v52, v52, s0
	ds_write_b16 v51, v52 offset:42768
	v_mul_f32_e32 v53, v57, v54
	v_lshlrev_b32_e32 v52, 16, v70
	v_mul_f32_e32 v54, 0xbfb8aa3b, v52
	v_exp_f32_e32 v54, v54
	s_nop 0
	v_add_f32_e32 v54, 1.0, v54
	v_rcp_f32_e32 v54, v54
	s_nop 0
	v_mul_f32_e32 v52, v54, v52
	v_mul_f32_e32 v52, v53, v52
	v_cvt_pk_bf16_f32 v52, v52, s0
	ds_write_b16 v51, v52 offset:43296
	v_mul_f32_e32 v53, v57, v55
	v_lshlrev_b32_e32 v52, 16, v72
	v_mul_f32_e32 v54, 0xbfb8aa3b, v52
	v_exp_f32_e32 v54, v54
	s_nop 0
	v_add_f32_e32 v54, 1.0, v54
	v_rcp_f32_e32 v54, v54
	s_nop 0
	v_mul_f32_e32 v52, v54, v52
	v_mul_f32_e32 v52, v53, v52
	v_cvt_pk_bf16_f32 v52, v52, s0
	ds_write_b16 v51, v52 offset:43824
	v_mfma_f32_16x16x32_bf16 v[52:55], v[24:27], v[16:19], 0
	v_mfma_f32_16x16x32_bf16 v[16:19], v[8:11], v[16:19], 0
	v_mfma_f32_16x16x32_bf16 v[52:55], v[28:31], v[20:23], v[52:55]
	v_mfma_f32_16x16x32_bf16 v[16:19], v[12:15], v[20:23], v[16:19]
	s_nop 0
	s_nop 5
	v_mul_f32_e32 v52, v57, v52
	v_mul_f32_e32 v53, v57, v53
	s_nop 0
	v_lshlrev_b32_e32 v20, 16, v73
	v_mul_f32_e32 v21, 0xbfb8aa3b, v20
	v_exp_f32_e32 v21, v21
	v_mul_f32_e32 v16, v57, v16
	v_mul_f32_e32 v17, v57, v17
	v_add_f32_e32 v21, 1.0, v21
	v_rcp_f32_e32 v21, v21
	s_nop 0
	v_mul_f32_e32 v20, v21, v20
	v_lshlrev_b32_e32 v56, 16, v71
	v_mul_f32_e32 v58, 0xbfb8aa3b, v56
	v_exp_f32_e32 v58, v58
	v_mul_f32_e32 v16, v16, v20
	v_cvt_pk_bf16_f32 v16, v16, s0
	ds_write_b16 v51, v16 offset:59136
	v_add_f32_e32 v58, 1.0, v58
	v_rcp_f32_e32 v58, v58
	s_nop 0
	v_lshlrev_b32_e32 v21, 16, v74
	v_mul_f32_e32 v22, 0xbfb8aa3b, v21
	v_mul_f32_e32 v56, v58, v56
	v_mul_f32_e32 v52, v52, v56
	v_cvt_pk_bf16_f32 v52, v52, s0
	ds_write_b16 v51, v52 offset:50688
	v_lshlrev_b32_e32 v16, 16, v75
	v_mul_f32_e32 v20, 0xbfb8aa3b, v16
	v_exp_f32_e32 v20, v20
	v_exp_f32_e32 v22, v22
	v_add_f32_e32 v20, 1.0, v20
	v_rcp_f32_e32 v20, v20
	v_add_f32_e32 v22, 1.0, v22
	v_rcp_f32_e32 v22, v22
	v_mul_f32_e32 v16, v20, v16
	global_load_dword v20, v[48:49], off offset:64
	v_mul_f32_e32 v16, v17, v16
	v_cvt_pk_bf16_f32 v16, v16, s0
	ds_write_b16 v51, v16 offset:59664
	v_mul_f32_e32 v17, v57, v18
	v_mul_f32_e32 v21, v22, v21
	v_lshlrev_b32_e32 v16, 16, v77
	v_mul_f32_e32 v18, 0xbfb8aa3b, v16
	v_exp_f32_e32 v18, v18
	s_nop 0
	v_add_f32_e32 v18, 1.0, v18
	v_rcp_f32_e32 v18, v18
	s_nop 0
	v_mul_f32_e32 v16, v18, v16
	v_mul_f32_e32 v16, v17, v16
	v_cvt_pk_bf16_f32 v16, v16, s0
	ds_write_b16 v51, v16 offset:60192
	v_mul_f32_e32 v17, v57, v19
	v_lshlrev_b32_e32 v16, 16, v78
	v_mul_f32_e32 v18, 0xbfb8aa3b, v16
	v_exp_f32_e32 v18, v18
	s_nop 0
	v_add_f32_e32 v18, 1.0, v18
	v_rcp_f32_e32 v18, v18
	s_nop 0
	v_mul_f32_e32 v16, v18, v16
	v_mul_f32_e32 v16, v17, v16
	v_cvt_pk_bf16_f32 v16, v16, s0
	ds_write_b16 v51, v16 offset:60720
	v_mfma_f32_16x16x32_bf16 v[16:19], v[40:43], v[0:3], 0
	v_mfma_f32_16x16x32_bf16 v[16:19], v[44:47], v[4:7], v[16:19]
	s_waitcnt vmcnt(0)
	s_nop 6
	v_mul_f32_e32 v16, v20, v16
	v_mul_f32_e32 v16, v16, v21
	v_cvt_pk_bf16_f32 v16, v16, s0
	ds_write_b16 v51, v16 offset:33824
	s_nop 0
	v_mul_f32_e32 v17, v20, v17
	v_lshlrev_b32_e32 v52, 16, v76
	v_mul_f32_e32 v56, 0xbfb8aa3b, v52
	v_exp_f32_e32 v56, v56
	s_nop 0
	v_lshlrev_b32_e32 v16, 16, v79
	v_mul_f32_e32 v21, 0xbfb8aa3b, v16
	v_exp_f32_e32 v21, v21
	v_add_f32_e32 v56, 1.0, v56
	v_rcp_f32_e32 v56, v56
	v_add_f32_e32 v21, 1.0, v21
	v_rcp_f32_e32 v21, v21
	v_mul_f32_e32 v52, v56, v52
	v_mul_f32_e32 v52, v53, v52
	v_cvt_pk_bf16_f32 v52, v52, s0
	v_mul_f32_e32 v16, v21, v16
	v_mul_f32_e32 v16, v17, v16
	v_cvt_pk_bf16_f32 v16, v16, s0
	ds_write_b16 v51, v16 offset:34352
	v_mul_f32_e32 v17, v20, v18
	ds_write_b16 v51, v52 offset:51216
	v_lshlrev_b32_e32 v16, 16, v80
	v_mul_f32_e32 v18, 0xbfb8aa3b, v16
	v_exp_f32_e32 v18, v18
	s_nop 0
	v_lshlrev_b32_e32 v21, 16, v81
	v_mul_f32_e32 v53, v57, v54
	v_mul_f32_e32 v22, 0xbfb8aa3b, v21
	v_add_f32_e32 v18, 1.0, v18
	v_rcp_f32_e32 v18, v18
	v_exp_f32_e32 v22, v22
	v_mul_f32_e32 v16, v18, v16
	v_mul_f32_e32 v16, v17, v16
	v_cvt_pk_bf16_f32 v16, v16, s0
	ds_write_b16 v51, v16 offset:34880
	v_lshlrev_b32_e32 v52, 16, v82
	v_mul_f32_e32 v17, v20, v19
	v_mul_f32_e32 v54, 0xbfb8aa3b, v52
	v_exp_f32_e32 v54, v54
	s_nop 0
	v_lshlrev_b32_e32 v16, 16, v83
	v_mul_f32_e32 v18, 0xbfb8aa3b, v16
	v_exp_f32_e32 v18, v18
	v_add_f32_e32 v54, 1.0, v54
	v_add_f32_e32 v22, 1.0, v22
	v_rcp_f32_e32 v54, v54
	v_add_f32_e32 v18, 1.0, v18
	v_rcp_f32_e32 v18, v18
	v_rcp_f32_e32 v22, v22
	v_mul_f32_e32 v52, v54, v52
	v_mul_f32_e32 v52, v53, v52
	v_mul_f32_e32 v16, v18, v16
	v_mul_f32_e32 v16, v17, v16
	v_cvt_pk_bf16_f32 v16, v16, s0
	ds_write_b16 v51, v16 offset:35408
	v_mfma_f32_16x16x32_bf16 v[16:19], v[32:35], v[0:3], 0
	v_mul_f32_e32 v21, v22, v21
	v_cvt_pk_bf16_f32 v52, v52, s0
	ds_write_b16 v51, v52 offset:51744
	v_mfma_f32_16x16x32_bf16 v[16:19], v[36:39], v[4:7], v[16:19]
	s_nop 0
	v_mul_f32_e32 v53, v57, v55
	s_nop 5
	v_mul_f32_e32 v16, v20, v16
	v_mul_f32_e32 v16, v16, v21
	v_cvt_pk_bf16_f32 v16, v16, s0
	ds_write_b16 v51, v16 offset:42272
	s_nop 0
	v_mul_f32_e32 v17, v20, v17
	s_nop 0
	v_lshlrev_b32_e32 v52, 16, v84
	v_mul_f32_e32 v54, 0xbfb8aa3b, v52
	v_exp_f32_e32 v54, v54
	s_nop 0
	v_lshlrev_b32_e32 v16, 16, v85
	v_mul_f32_e32 v21, 0xbfb8aa3b, v16
	v_exp_f32_e32 v21, v21
	v_add_f32_e32 v54, 1.0, v54
	v_rcp_f32_e32 v54, v54
	v_add_f32_e32 v21, 1.0, v21
	v_rcp_f32_e32 v21, v21
	v_mul_f32_e32 v52, v54, v52
	v_mul_f32_e32 v52, v53, v52
	v_cvt_pk_bf16_f32 v52, v52, s0
	v_mul_f32_e32 v16, v21, v16
	v_mul_f32_e32 v16, v17, v16
	v_cvt_pk_bf16_f32 v16, v16, s0
	ds_write_b16 v51, v16 offset:42800
	v_mul_f32_e32 v17, v20, v18
	ds_write_b16 v51, v52 offset:52272
	v_lshlrev_b32_e32 v16, 16, v86
	v_mul_f32_e32 v18, 0xbfb8aa3b, v16
	v_exp_f32_e32 v18, v18
	s_nop 0
	v_lshlrev_b32_e32 v21, 16, v87
	v_mul_f32_e32 v22, 0xbfb8aa3b, v21
	v_exp_f32_e32 v22, v22
	v_add_f32_e32 v18, 1.0, v18
	v_rcp_f32_e32 v18, v18
	v_add_f32_e32 v22, 1.0, v22
	v_rcp_f32_e32 v22, v22
	v_mul_f32_e32 v16, v18, v16
	v_mul_f32_e32 v16, v17, v16
	v_cvt_pk_bf16_f32 v16, v16, s0
	ds_write_b16 v51, v16 offset:43328
	v_mul_f32_e32 v17, v20, v19
	v_mul_f32_e32 v21, v22, v21
	v_lshlrev_b32_e32 v16, 16, v88
	v_mul_f32_e32 v18, 0xbfb8aa3b, v16
	v_exp_f32_e32 v18, v18
	s_nop 0
	v_add_f32_e32 v18, 1.0, v18
	v_rcp_f32_e32 v18, v18
	s_nop 0
	v_mul_f32_e32 v16, v18, v16
	v_mul_f32_e32 v16, v17, v16
	v_cvt_pk_bf16_f32 v16, v16, s0
	ds_write_b16 v51, v16 offset:43856
	v_mfma_f32_16x16x32_bf16 v[16:19], v[24:27], v[0:3], 0
	v_mfma_f32_16x16x32_bf16 v[16:19], v[28:31], v[4:7], v[16:19]
	v_mfma_f32_16x16x32_bf16 v[0:3], v[8:11], v[0:3], 0
	v_mfma_f32_16x16x32_bf16 v[0:3], v[12:15], v[4:7], v[0:3]
	s_nop 5
	v_mul_f32_e32 v16, v20, v16
	v_mul_f32_e32 v16, v16, v21
	v_cvt_pk_bf16_f32 v16, v16, s0
	ds_write_b16 v51, v16 offset:50720
	s_nop 0
	s_nop 0
	v_mul_f32_e32 v17, v20, v17
	v_mul_f32_e32 v0, v20, v0
	v_mul_f32_e32 v1, v20, v1
	s_nop 0
	v_lshlrev_b32_e32 v16, 16, v89
	v_lshlrev_b32_e32 v4, 16, v90
	v_mul_f32_e32 v21, 0xbfb8aa3b, v16
	v_mul_f32_e32 v5, 0xbfb8aa3b, v4
	v_exp_f32_e32 v21, v21
	v_exp_f32_e32 v5, v5
	v_add_f32_e32 v21, 1.0, v21
	v_add_f32_e32 v5, 1.0, v5
	v_rcp_f32_e32 v21, v21
	v_rcp_f32_e32 v5, v5
	v_mul_f32_e32 v16, v21, v16
	v_mul_f32_e32 v4, v5, v4
	v_mul_f32_e32 v16, v17, v16
	v_mul_f32_e32 v0, v0, v4
	v_cvt_pk_bf16_f32 v16, v16, s0
	v_cvt_pk_bf16_f32 v0, v0, s0
	ds_write_b16 v51, v16 offset:51248
	ds_write_b16 v51, v0 offset:59168
	v_mul_f32_e32 v17, v20, v18
	v_lshlrev_b32_e32 v16, 16, v91
	v_mul_f32_e32 v18, 0xbfb8aa3b, v16
	v_lshlrev_b32_e32 v0, 16, v92
	v_mul_f32_e32 v4, 0xbfb8aa3b, v0
	v_exp_f32_e32 v18, v18
	v_exp_f32_e32 v4, v4
	v_add_f32_e32 v18, 1.0, v18
	v_add_f32_e32 v4, 1.0, v4
	v_rcp_f32_e32 v18, v18
	v_rcp_f32_e32 v4, v4
	v_mul_f32_e32 v16, v18, v16
	v_mul_f32_e32 v0, v4, v0
	v_mul_f32_e32 v16, v17, v16
	v_mul_f32_e32 v0, v1, v0
	v_cvt_pk_bf16_f32 v16, v16, s0
	v_cvt_pk_bf16_f32 v0, v0, s0
	ds_write_b16 v51, v16 offset:51776
	ds_write_b16 v51, v0 offset:59696
	v_mul_f32_e32 v1, v20, v2
	v_mul_f32_e32 v17, v20, v19
	v_lshlrev_b32_e32 v16, 16, v93
	v_mul_f32_e32 v18, 0xbfb8aa3b, v16
	v_lshlrev_b32_e32 v0, 16, v94
	v_mul_f32_e32 v2, 0xbfb8aa3b, v0
	v_exp_f32_e32 v2, v2
	v_exp_f32_e32 v18, v18
	v_add_f32_e32 v2, 1.0, v2
	v_rcp_f32_e32 v2, v2
	v_add_f32_e32 v18, 1.0, v18
	v_rcp_f32_e32 v18, v18
	v_mul_f32_e32 v0, v2, v0
	v_mul_f32_e32 v0, v1, v0
	v_cvt_pk_bf16_f32 v0, v0, s0
	ds_write_b16 v51, v0 offset:60224
	v_mul_f32_e32 v1, v20, v3
	v_mul_f32_e32 v16, v18, v16
	v_mul_f32_e32 v16, v17, v16
	v_cvt_pk_bf16_f32 v16, v16, s0
	v_lshlrev_b32_e32 v0, 16, v95
	v_mul_f32_e32 v2, 0xbfb8aa3b, v0
	v_exp_f32_e32 v2, v2
	ds_write_b16 v51, v16 offset:52304
	v_add_f32_e32 v2, 1.0, v2
	v_rcp_f32_e32 v2, v2
	s_nop 0
	v_mul_f32_e32 v0, v2, v0
	v_mul_f32_e32 v0, v1, v0
	v_cvt_pk_bf16_f32 v0, v0, s0
	ds_write_b16 v51, v0 offset:60752
	v_ashrrev_i32_e32 v0, 31, v50
	v_lshrrev_b32_e32 v0, 27, v0
	v_add_u32_e32 v0, v50, v0
	v_ashrrev_i32_e32 v2, 5, v0
	v_and_b32_e32 v0, 0xffffffe0, v0
	v_sub_u32_e32 v3, v50, v0
	v_lshlrev_b32_e32 v0, 3, v3
	v_add_u32_e32 v6, s44, v2
	v_ashrrev_i32_e32 v1, 31, v0
	v_ashrrev_i32_e32 v7, 31, v6
	v_lshl_add_u64 v[4:5], v[0:1], 1, s[26:27]
	v_lshlrev_b64 v[0:1], 11, v[6:7]
	v_lshlrev_b32_e32 v3, 4, v3
	v_lshl_add_u64 v[8:9], v[4:5], 0, v[0:1]
	v_mul_lo_u32 v0, v2, s48
	v_add3_u32 v7, 0, v3, v0
	s_waitcnt lgkmcnt(0)
	s_barrier
	ds_read_b128 v[0:3], v7 offset:33792
	s_waitcnt lgkmcnt(0)
	global_store_dwordx4 v[8:9], v[0:3], off sc1
	s_nop 1
	v_add_u32_e32 v0, 16, v6
	v_ashrrev_i32_e32 v1, 31, v0
	v_lshlrev_b64 v[0:1], 11, v[0:1]
	v_lshl_add_u64 v[8:9], v[4:5], 0, v[0:1]
	ds_read_b128 v[0:3], v7 offset:42240
	s_waitcnt lgkmcnt(0)
	global_store_dwordx4 v[8:9], v[0:3], off sc1
	s_nop 1
	v_add_u32_e32 v0, 32, v6
	v_ashrrev_i32_e32 v1, 31, v0
	v_lshlrev_b64 v[0:1], 11, v[0:1]
	v_lshl_add_u64 v[8:9], v[4:5], 0, v[0:1]
	ds_read_b128 v[0:3], v7 offset:50688
	s_waitcnt lgkmcnt(0)
	global_store_dwordx4 v[8:9], v[0:3], off sc1
	s_nop 1
	v_add_u32_e32 v0, 48, v6
	v_ashrrev_i32_e32 v1, 31, v0
	v_lshlrev_b64 v[0:1], 11, v[0:1]
	v_lshl_add_u64 v[4:5], v[4:5], 0, v[0:1]
	ds_read_b128 v[0:3], v7 offset:59136
	s_waitcnt lgkmcnt(0)
	global_store_dwordx4 v[4:5], v[0:3], off sc1
	s_nop 1
	v_mov_b32_e32 v0, v147
	s_barrier
	s_branch .LBB0_641

.LBB0_646:
	s_mov_b64 s[58:59], s[94:95]
	s_mov_b64 s[26:27], -1
	s_and_b64 vcc, exec, s[30:31]
	s_cbranch_vccnz .LBB0_514
	s_branch .LBB0_515
.LBB0_660:
	s_waitcnt vmcnt(4)
	v_lshlrev_b32_e32 v136, 16, v60
	v_and_b32_e32 v60, 0xffff0000, v60
	v_mul_f32_e32 v60, 0xbfb8aa3b, v60
	v_exp_f32_e32 v60, v60
	v_mul_f32_e32 v136, 0xbfb8aa3b, v136
	v_exp_f32_e32 v136, v136
	v_lshlrev_b32_e32 v138, 16, v56
	v_add_f32_e32 v60, 1.0, v60
	v_rcp_f32_e32 v137, v60
	v_lshlrev_b32_e32 v60, 16, v61
	v_and_b32_e32 v61, 0xffff0000, v61
	v_mul_f32_e32 v60, 0xbfb8aa3b, v60
	v_mul_f32_e32 v61, 0xbfb8aa3b, v61
	v_exp_f32_e32 v60, v60
	v_exp_f32_e32 v61, v61
	v_add_f32_e32 v136, 1.0, v136
	v_rcp_f32_e32 v136, v136
	v_add_f32_e32 v60, 1.0, v60
	v_add_f32_e32 v61, 1.0, v61
	v_rcp_f32_e32 v60, v60
	v_rcp_f32_e32 v61, v61
	v_and_b32_e32 v139, 0xffff0000, v56
	v_pk_mul_f32 v[136:137], v[136:137], v[138:139]
	s_nop 0
	v_cvt_pk_bf16_f32 v56, v136, v137
	v_lshlrev_b32_e32 v136, 16, v57
	v_and_b32_e32 v137, 0xffff0000, v57
	v_pk_mul_f32 v[60:61], v[60:61], v[136:137]
	v_lshlrev_b32_e32 v136, 16, v58
	v_cvt_pk_bf16_f32 v57, v60, v61
	v_lshlrev_b32_e32 v60, 16, v62
	v_and_b32_e32 v61, 0xffff0000, v62
	v_mul_f32_e32 v60, 0xbfb8aa3b, v60
	v_mul_f32_e32 v61, 0xbfb8aa3b, v61
	v_exp_f32_e32 v60, v60
	v_exp_f32_e32 v61, v61
	v_and_b32_e32 v137, 0xffff0000, v58
	v_lshlrev_b32_e32 v62, 16, v59
	v_add_f32_e32 v60, 1.0, v60
	v_add_f32_e32 v61, 1.0, v61
	v_rcp_f32_e32 v60, v60
	v_rcp_f32_e32 v61, v61
	s_nop 0
	v_pk_mul_f32 v[60:61], v[60:61], v[136:137]
	s_nop 0
	v_cvt_pk_bf16_f32 v58, v60, v61
	v_lshlrev_b32_e32 v60, 16, v63
	v_and_b32_e32 v61, 0xffff0000, v63
	v_mul_f32_e32 v60, 0xbfb8aa3b, v60
	v_mul_f32_e32 v61, 0xbfb8aa3b, v61
	v_exp_f32_e32 v60, v60
	v_exp_f32_e32 v61, v61
	v_and_b32_e32 v63, 0xffff0000, v59
	v_add_f32_e32 v60, 1.0, v60
	v_add_f32_e32 v61, 1.0, v61
	v_rcp_f32_e32 v60, v60
	v_rcp_f32_e32 v61, v61
	s_nop 0
	v_pk_mul_f32 v[60:61], v[60:61], v[62:63]
	s_nop 0
	v_cvt_pk_bf16_f32 v59, v60, v61
	v_lshl_add_u32 v60, v128, 9, v131
	ds_write_b128 v60, v[56:59]
	s_or_b64 exec, exec, s[26:27]
	s_and_saveexec_b64 s[26:27], s[50:51]
	s_cbranch_execz .LBB0_580
